# v61 + latent attention main loop: 16 v_mov_b64 copies of -m dropped, QK MFMAs for the second key row-block take -m directly as C operand
# speedup vs baseline: 1.0116x; 1.0116x over previous
.LBB0_362:
	s_and_b32 s14, s11, 1
	s_mul_i32 s12, s14, 0x4600
	s_add_i32 s15, s12, 16
	v_add3_u32 v160, s15, v209, v214
	ds_read_b128 v[96:99], v160
	ds_read_b128 v[224:227], v160 offset:4608
	ds_read_b128 v[228:231], v160 offset:32
	ds_read_b128 v[232:235], v160 offset:4640
	ds_read_b128 v[240:243], v160 offset:64
	ds_read_b128 v[248:251], v160 offset:4672
	s_waitcnt lgkmcnt(5)
	v_mfma_f32_32x32x16_bf16 v[144:159], v[96:99], v[162:165], v[48:63]
	v_mfma_f32_32x32x16_bf16 v[128:143], v[96:99], v[166:169], v[80:95]
	s_waitcnt lgkmcnt(4)
	v_mfma_f32_32x32x16_bf16 v[112:127], v[224:227], v[162:165], v[48:63]
	s_nop 0
	v_mfma_f32_32x32x16_bf16 v[96:111], v[224:227], v[166:169], v[80:95]
	ds_read_b128 v[224:227], v160 offset:96
	s_waitcnt lgkmcnt(4)
	v_mfma_f32_32x32x16_bf16 v[144:159], v[228:231], v[170:173], v[144:159]
	s_waitcnt lgkmcnt(3)
	v_mfma_f32_32x32x16_bf16 v[112:127], v[232:235], v[170:173], v[112:127]
	v_mfma_f32_32x32x16_bf16 v[128:143], v[228:231], v[174:177], v[128:143]
	v_mfma_f32_32x32x16_bf16 v[96:111], v[232:235], v[174:177], v[96:111]
	ds_read_b128 v[228:231], v160 offset:4704
	s_waitcnt lgkmcnt(3)
	v_mfma_f32_32x32x16_bf16 v[144:159], v[240:243], v[178:181], v[144:159]
	s_waitcnt lgkmcnt(2)
	v_mfma_f32_32x32x16_bf16 v[112:127], v[248:251], v[178:181], v[112:127]
	v_mfma_f32_32x32x16_bf16 v[128:143], v[240:243], v[186:189], v[128:143]
	v_mfma_f32_32x32x16_bf16 v[96:111], v[248:251], v[186:189], v[96:111]
	v_add3_u32 v240, s15, v211, v210
	v_add_u32_e32 v241, 0x3000, v240
	v_add_u32_e32 v240, 0x2000, v240
	ds_read2_b64 v[232:235], v240 offset0:128 offset1:130
	ds_read2_b64 v[248:251], v241 offset0:160 offset1:162
	s_waitcnt lgkmcnt(3)
	v_mfma_f32_32x32x16_bf16 v[144:159], v[224:227], v[182:185], v[144:159]
	s_waitcnt lgkmcnt(2)
	v_mfma_f32_32x32x16_bf16 v[112:127], v[228:231], v[182:185], v[112:127]
	s_nop 9
	v_max_f32_e32 v160, v145, v145
	v_max_f32_e32 v215, v144, v144
	v_max_f32_e32 v160, v215, v160
	v_mfma_f32_32x32x16_bf16 v[128:143], v[224:227], v[190:193], v[128:143]
	v_max3_f32 v215, v146, v147, v113
	v_max3_f32 v160, v160, v112, v114
	v_max3_f32 v160, v160, v115, v148
	v_max3_f32 v215, v215, v150, v151
	v_max3_f32 v160, v160, v149, v116
	v_max3_f32 v215, v215, v118, v119
	v_max3_f32 v160, v160, v117, v152
	v_max3_f32 v215, v215, v154, v155
	v_max3_f32 v160, v160, v153, v120
	v_max3_f32 v215, v215, v122, v123
	v_mfma_f32_32x32x16_bf16 v[96:111], v[228:231], v[190:193], v[96:111]
	v_max3_f32 v160, v160, v121, v156
	v_max3_f32 v215, v215, v158, v159
	v_max3_f32 v160, v160, v157, v124
	v_max3_f32 v215, v215, v126, v127
	v_max3_f32 v160, v160, v125, v215
	v_mov_b32_e32 v215, v160
	s_nop 1
	v_permlane32_swap_b32_e32 v160, v215
	v_max_f32_e32 v215, v215, v215
	v_max_f32_e32 v160, v160, v160
	v_max_f32_e32 v160, v160, v215
	v_cmp_lt_f32_e32 vcc, s17, v160
	s_cbranch_vccz .LBB0_364
	v_max_f32_e32 v48, v160, v160
	v_max_f32_e32 v50, 0, v48
	v_exp_f32_e64 v51, -v50
	s_nop 0
	v_pk_add_f32 v[52:53], v[216:217], v[50:51]
	v_pk_mul_f32 v[48:49], v[216:217], v[50:51]
	v_pk_add_f32 v[144:145], v[144:145], v[50:51] op_sel_hi:[1,0] neg_lo:[0,1] neg_hi:[0,1]
	v_mov_b32_e32 v53, v49
	v_pk_add_f32 v[112:113], v[112:113], v[50:51] op_sel_hi:[1,0] neg_lo:[0,1] neg_hi:[0,1]
	v_pk_add_f32 v[48:49], v[52:53], 0 neg_lo:[1,1] neg_hi:[1,1]
	v_pk_add_f32 v[146:147], v[146:147], v[50:51] op_sel_hi:[1,0] neg_lo:[0,1] neg_hi:[0,1]
	v_pk_add_f32 v[114:115], v[114:115], v[50:51] op_sel_hi:[1,0] neg_lo:[0,1] neg_hi:[0,1]
	v_pk_add_f32 v[148:149], v[148:149], v[50:51] op_sel_hi:[1,0] neg_lo:[0,1] neg_hi:[0,1]
	v_pk_add_f32 v[116:117], v[116:117], v[50:51] op_sel_hi:[1,0] neg_lo:[0,1] neg_hi:[0,1]
	v_pk_add_f32 v[150:151], v[150:151], v[50:51] op_sel_hi:[1,0] neg_lo:[0,1] neg_hi:[0,1]
	v_pk_add_f32 v[118:119], v[118:119], v[50:51] op_sel_hi:[1,0] neg_lo:[0,1] neg_hi:[0,1]
	v_pk_add_f32 v[152:153], v[152:153], v[50:51] op_sel_hi:[1,0] neg_lo:[0,1] neg_hi:[0,1]
	v_pk_add_f32 v[120:121], v[120:121], v[50:51] op_sel_hi:[1,0] neg_lo:[0,1] neg_hi:[0,1]
	v_pk_add_f32 v[154:155], v[154:155], v[50:51] op_sel_hi:[1,0] neg_lo:[0,1] neg_hi:[0,1]
	v_pk_add_f32 v[122:123], v[122:123], v[50:51] op_sel_hi:[1,0] neg_lo:[0,1] neg_hi:[0,1]
	v_pk_add_f32 v[156:157], v[156:157], v[50:51] op_sel_hi:[1,0] neg_lo:[0,1] neg_hi:[0,1]
	v_pk_add_f32 v[124:125], v[124:125], v[50:51] op_sel_hi:[1,0] neg_lo:[0,1] neg_hi:[0,1]
	v_pk_add_f32 v[158:159], v[158:159], v[50:51] op_sel_hi:[1,0] neg_lo:[0,1] neg_hi:[0,1]
	v_pk_add_f32 v[126:127], v[126:127], v[50:51] op_sel_hi:[1,0] neg_lo:[0,1] neg_hi:[0,1]
	v_mov_b32_e32 v50, v51
	v_pk_mul_f32 v[78:79], v[78:79], v[50:51] op_sel_hi:[1,0]
	v_pk_mul_f32 v[76:77], v[76:77], v[50:51] op_sel_hi:[1,0]
	v_pk_mul_f32 v[74:75], v[74:75], v[50:51] op_sel_hi:[1,0]
	v_pk_mul_f32 v[72:73], v[72:73], v[50:51] op_sel_hi:[1,0]
	v_pk_mul_f32 v[70:71], v[70:71], v[50:51] op_sel_hi:[1,0]
	v_pk_mul_f32 v[68:69], v[68:69], v[50:51] op_sel_hi:[1,0]
	v_pk_mul_f32 v[66:67], v[66:67], v[50:51] op_sel_hi:[1,0]
	v_pk_mul_f32 v[64:65], v[64:65], v[50:51] op_sel_hi:[1,0]
	v_pk_mul_f32 v[14:15], v[14:15], v[50:51] op_sel_hi:[1,0]
	v_pk_mul_f32 v[12:13], v[12:13], v[50:51] op_sel_hi:[1,0]
	v_pk_mul_f32 v[10:11], v[10:11], v[50:51] op_sel_hi:[1,0]
	v_pk_mul_f32 v[8:9], v[8:9], v[50:51] op_sel_hi:[1,0]
	v_pk_mul_f32 v[6:7], v[6:7], v[50:51] op_sel_hi:[1,0]
	v_pk_mul_f32 v[4:5], v[4:5], v[50:51] op_sel_hi:[1,0]
	v_pk_mul_f32 v[2:3], v[2:3], v[50:51] op_sel_hi:[1,0]
	v_pk_mul_f32 v[0:1], v[0:1], v[50:51] op_sel_hi:[1,0]
	v_mov_b64_e32 v[216:217], v[52:53]
	v_mov_b32_e32 v49, v48
	v_mov_b32_e32 v50, v48
	v_mov_b32_e32 v51, v48
	v_mov_b32_e32 v52, v48
	v_mov_b32_e32 v53, v48
	v_mov_b32_e32 v54, v48
	v_mov_b32_e32 v55, v48
	v_mov_b32_e32 v56, v48
	v_mov_b32_e32 v57, v48
	v_mov_b32_e32 v58, v48
	v_mov_b32_e32 v59, v48
	v_mov_b32_e32 v60, v48
	v_mov_b32_e32 v61, v48
	v_mov_b32_e32 v62, v48
	v_mov_b32_e32 v63, v48
